# v075 + permlane swaps instead of ds_bpermute for the row-sum shuffles in the EpiRes / EpiCI / Down epilogues as well (39 more sites, partial lgkmcnt waits recounted)
# speedup vs baseline: 1.0287x; 1.0287x over previous
.LBB0_134:
	s_add_u32 s28, s66, 0xfffc0080
	s_addc_u32 s29, s67, -1
	s_add_i32 s88, 0, 0x10000
	ds_read_b128 v[128:131], v172
	ds_read_b128 v[132:135], v172 offset:1024
	ds_read_b128 v[148:151], v172 offset:2048
	ds_read_b128 v[152:155], v172 offset:3072
	s_cmp_eq_u32 vcc_lo, 12
	s_cselect_b32 s71, s5, s29
	s_cselect_b32 s70, s7, s28
	s_cselect_b32 s69, s17, s91
	s_cselect_b32 s68, s19, s85
	s_add_i32 m0, s73, 0xc000
	ds_read_b128 v[156:159], v192
	ds_read_b128 v[164:167], v192 offset:2048
	ds_read_b128 v[194:197], v192 offset:4096
	ds_read_b128 v[202:205], v192 offset:6144
	ds_read_b128 v[160:163], v192 offset:1024
	ds_read_b128 v[168:171], v192 offset:3072
	ds_read_b128 v[198:201], v192 offset:5120
	ds_read_b128 v[206:209], v192 offset:7168
	global_load_lds_dwordx4 v144, s[66:67]
	s_add_i32 m0, s73, 0xe000
	s_nop 0
	global_load_lds_dwordx4 v146, s[66:67]
	s_waitcnt lgkmcnt(8)
	s_barrier
	s_waitcnt lgkmcnt(7)
	v_mfma_f32_16x16x32_bf16 v[124:127], v[128:131], v[156:159], v[124:127]
	v_mfma_f32_16x16x32_bf16 v[120:123], v[148:151], v[156:159], v[120:123]
	s_waitcnt lgkmcnt(6)
	v_mfma_f32_16x16x32_bf16 v[108:111], v[128:131], v[164:167], v[108:111]
	v_mfma_f32_16x16x32_bf16 v[104:107], v[148:151], v[164:167], v[104:107]
	s_waitcnt lgkmcnt(5)
	v_mfma_f32_16x16x32_bf16 v[92:95], v[128:131], v[194:197], v[92:95]
	v_mfma_f32_16x16x32_bf16 v[88:91], v[148:151], v[194:197], v[88:91]
	s_waitcnt lgkmcnt(4)
	v_mfma_f32_16x16x32_bf16 v[76:79], v[128:131], v[202:205], v[76:79]
	v_mfma_f32_16x16x32_bf16 v[72:75], v[148:151], v[202:205], v[72:75]
	s_waitcnt lgkmcnt(3)
	v_mfma_f32_16x16x32_bf16 v[124:127], v[132:135], v[160:163], v[124:127]
	v_mfma_f32_16x16x32_bf16 v[120:123], v[152:155], v[160:163], v[120:123]
	s_waitcnt lgkmcnt(2)
	v_mfma_f32_16x16x32_bf16 v[108:111], v[132:135], v[168:171], v[108:111]
	v_mfma_f32_16x16x32_bf16 v[104:107], v[152:155], v[168:171], v[104:107]
	s_waitcnt lgkmcnt(1)
	v_mfma_f32_16x16x32_bf16 v[92:95], v[132:135], v[198:201], v[92:95]
	v_mfma_f32_16x16x32_bf16 v[88:91], v[152:155], v[198:201], v[88:91]
	s_waitcnt lgkmcnt(0)
	v_mfma_f32_16x16x32_bf16 v[76:79], v[132:135], v[206:209], v[76:79]
	v_mfma_f32_16x16x32_bf16 v[72:75], v[152:155], v[206:209], v[72:75]
	s_barrier
	s_add_i32 s89, 0, 0x14000
	s_add_i32 s28, s88, s72
	ds_read_b128 v[210:213], v172 offset:16384
	ds_read_b128 v[214:217], v172 offset:17408
	ds_read_b128 v[232:235], v172 offset:18432
	ds_read_b128 v[236:239], v172 offset:19456
	s_mov_b32 m0, s28
	s_nop 0
	global_load_lds_dwordx4 v138, s[68:69]
	s_add_i32 m0, s28, 0x2000
	s_nop 0
	global_load_lds_dwordx4 v142, s[68:69]
	s_barrier
	s_waitcnt lgkmcnt(3)
	v_mfma_f32_16x16x32_bf16 v[116:119], v[210:213], v[156:159], v[116:119]
	s_waitcnt lgkmcnt(1)
	v_mfma_f32_16x16x32_bf16 v[112:115], v[232:235], v[156:159], v[112:115]
	v_mfma_f32_16x16x32_bf16 v[100:103], v[210:213], v[164:167], v[100:103]
	v_mfma_f32_16x16x32_bf16 v[96:99], v[232:235], v[164:167], v[96:99]
	v_mfma_f32_16x16x32_bf16 v[84:87], v[210:213], v[194:197], v[84:87]
	v_mfma_f32_16x16x32_bf16 v[80:83], v[232:235], v[194:197], v[80:83]
	v_mfma_f32_16x16x32_bf16 v[68:71], v[210:213], v[202:205], v[68:71]
	v_mfma_f32_16x16x32_bf16 v[64:67], v[232:235], v[202:205], v[64:67]
	v_mfma_f32_16x16x32_bf16 v[116:119], v[214:217], v[160:163], v[116:119]
	s_waitcnt lgkmcnt(0)
	v_mfma_f32_16x16x32_bf16 v[112:115], v[236:239], v[160:163], v[112:115]
	v_mfma_f32_16x16x32_bf16 v[100:103], v[214:217], v[168:171], v[100:103]
	v_mfma_f32_16x16x32_bf16 v[96:99], v[236:239], v[168:171], v[96:99]
	v_mfma_f32_16x16x32_bf16 v[84:87], v[214:217], v[198:201], v[84:87]
	v_mfma_f32_16x16x32_bf16 v[80:83], v[236:239], v[198:201], v[80:83]
	v_mfma_f32_16x16x32_bf16 v[68:71], v[214:217], v[206:209], v[68:71]
	v_mfma_f32_16x16x32_bf16 v[64:67], v[236:239], v[206:209], v[64:67]
	s_mov_b32 m0, s73
	s_barrier
	ds_read_b128 v[156:159], v192 offset:16384
	ds_read_b128 v[164:167], v192 offset:18432
	ds_read_b128 v[194:197], v192 offset:20480
	ds_read_b128 v[202:205], v192 offset:22528
	ds_read_b128 v[160:163], v192 offset:17408
	ds_read_b128 v[168:171], v192 offset:19456
	ds_read_b128 v[198:201], v192 offset:21504
	ds_read_b128 v[206:209], v192 offset:23552
	global_load_lds_dwordx4 v136, s[70:71]
	s_mov_b32 m0, s74
	s_nop 0
	global_load_lds_dwordx4 v140, s[70:71]
	s_barrier
	s_waitcnt lgkmcnt(7)
	v_mfma_f32_16x16x32_bf16 v[60:63], v[128:131], v[156:159], v[60:63]
	v_mfma_f32_16x16x32_bf16 v[56:59], v[148:151], v[156:159], v[56:59]
	s_waitcnt lgkmcnt(6)
	v_mfma_f32_16x16x32_bf16 v[44:47], v[128:131], v[164:167], v[44:47]
	v_mfma_f32_16x16x32_bf16 v[40:43], v[148:151], v[164:167], v[40:43]
	s_waitcnt lgkmcnt(5)
	v_mfma_f32_16x16x32_bf16 v[28:31], v[128:131], v[194:197], v[28:31]
	v_mfma_f32_16x16x32_bf16 v[24:27], v[148:151], v[194:197], v[24:27]
	s_waitcnt lgkmcnt(4)
	v_mfma_f32_16x16x32_bf16 v[12:15], v[128:131], v[202:205], v[12:15]
	v_mfma_f32_16x16x32_bf16 v[8:11], v[148:151], v[202:205], v[8:11]
	s_waitcnt lgkmcnt(3)
	v_mfma_f32_16x16x32_bf16 v[60:63], v[132:135], v[160:163], v[60:63]
	v_mfma_f32_16x16x32_bf16 v[56:59], v[152:155], v[160:163], v[56:59]
	s_waitcnt lgkmcnt(2)
	v_mfma_f32_16x16x32_bf16 v[44:47], v[132:135], v[168:171], v[44:47]
	v_mfma_f32_16x16x32_bf16 v[40:43], v[152:155], v[168:171], v[40:43]
	s_waitcnt lgkmcnt(1)
	v_mfma_f32_16x16x32_bf16 v[28:31], v[132:135], v[198:201], v[28:31]
	v_mfma_f32_16x16x32_bf16 v[24:27], v[152:155], v[198:201], v[24:27]
	s_waitcnt lgkmcnt(0)
	v_mfma_f32_16x16x32_bf16 v[12:15], v[132:135], v[206:209], v[12:15]
	v_mfma_f32_16x16x32_bf16 v[8:11], v[152:155], v[206:209], v[8:11]
	s_barrier
	s_add_u32 s28, s68, 0x40000
	s_addc_u32 s29, s69, 0
	s_add_i32 s88, s89, s72
	s_mov_b32 m0, s88
	s_nop 0
	global_load_lds_dwordx4 v138, s[28:29]
	s_add_i32 m0, s88, 0x2000
	s_nop 0
	global_load_lds_dwordx4 v142, s[28:29]
	s_waitcnt vmcnt(6)
	s_barrier
	v_mfma_f32_16x16x32_bf16 v[52:55], v[210:213], v[156:159], v[52:55]
	v_mfma_f32_16x16x32_bf16 v[48:51], v[232:235], v[156:159], v[48:51]
	v_mfma_f32_16x16x32_bf16 v[36:39], v[210:213], v[164:167], v[36:39]
	v_mfma_f32_16x16x32_bf16 v[32:35], v[232:235], v[164:167], v[32:35]
	v_mfma_f32_16x16x32_bf16 v[20:23], v[210:213], v[194:197], v[20:23]
	v_mfma_f32_16x16x32_bf16 v[16:19], v[232:235], v[194:197], v[16:19]
	v_mfma_f32_16x16x32_bf16 v[4:7], v[210:213], v[202:205], v[4:7]
	v_mfma_f32_16x16x32_bf16 v[0:3], v[232:235], v[202:205], v[0:3]
	v_mfma_f32_16x16x32_bf16 v[52:55], v[214:217], v[160:163], v[52:55]
	v_mfma_f32_16x16x32_bf16 v[48:51], v[236:239], v[160:163], v[48:51]
	v_mfma_f32_16x16x32_bf16 v[36:39], v[214:217], v[168:171], v[36:39]
	v_mfma_f32_16x16x32_bf16 v[32:35], v[236:239], v[168:171], v[32:35]
	v_mfma_f32_16x16x32_bf16 v[20:23], v[214:217], v[198:201], v[20:23]
	v_mfma_f32_16x16x32_bf16 v[16:19], v[236:239], v[198:201], v[16:19]
	v_mfma_f32_16x16x32_bf16 v[4:7], v[214:217], v[206:209], v[4:7]
	v_mfma_f32_16x16x32_bf16 v[0:3], v[236:239], v[206:209], v[0:3]
	s_add_i32 s88, 0, 0x18000
	s_barrier
	ds_read_b128 v[128:131], v172 offset:32768
	ds_read_b128 v[132:135], v172 offset:33792
	ds_read_b128 v[148:151], v172 offset:34816
	ds_read_b128 v[152:155], v172 offset:35840
	s_add_u32 s28, s70, 0x40000
	s_addc_u32 s29, s71, 0
	s_mov_b32 m0, s75
	ds_read_b128 v[156:159], v192 offset:32768
	ds_read_b128 v[164:167], v192 offset:34816
	ds_read_b128 v[194:197], v192 offset:36864
	ds_read_b128 v[202:205], v192 offset:38912
	ds_read_b128 v[160:163], v192 offset:33792
	ds_read_b128 v[168:171], v192 offset:35840
	ds_read_b128 v[198:201], v192 offset:37888
	ds_read_b128 v[206:209], v192 offset:39936
	global_load_lds_dwordx4 v136, s[28:29]
	s_mov_b32 m0, s76
	s_nop 0
	global_load_lds_dwordx4 v140, s[28:29]
	s_waitcnt lgkmcnt(8)
	s_barrier
	s_waitcnt lgkmcnt(7)
	v_mfma_f32_16x16x32_bf16 v[124:127], v[128:131], v[156:159], v[124:127]
	v_mfma_f32_16x16x32_bf16 v[120:123], v[148:151], v[156:159], v[120:123]
	s_waitcnt lgkmcnt(6)
	v_mfma_f32_16x16x32_bf16 v[108:111], v[128:131], v[164:167], v[108:111]
	v_mfma_f32_16x16x32_bf16 v[104:107], v[148:151], v[164:167], v[104:107]
	s_waitcnt lgkmcnt(5)
	v_mfma_f32_16x16x32_bf16 v[92:95], v[128:131], v[194:197], v[92:95]
	v_mfma_f32_16x16x32_bf16 v[88:91], v[148:151], v[194:197], v[88:91]
	s_waitcnt lgkmcnt(4)
	v_mfma_f32_16x16x32_bf16 v[76:79], v[128:131], v[202:205], v[76:79]
	v_mfma_f32_16x16x32_bf16 v[72:75], v[148:151], v[202:205], v[72:75]
	s_waitcnt lgkmcnt(3)
	v_mfma_f32_16x16x32_bf16 v[124:127], v[132:135], v[160:163], v[124:127]
	v_mfma_f32_16x16x32_bf16 v[120:123], v[152:155], v[160:163], v[120:123]
	s_waitcnt lgkmcnt(2)
	v_mfma_f32_16x16x32_bf16 v[108:111], v[132:135], v[168:171], v[108:111]
	v_mfma_f32_16x16x32_bf16 v[104:107], v[152:155], v[168:171], v[104:107]
	s_waitcnt lgkmcnt(1)
	v_mfma_f32_16x16x32_bf16 v[92:95], v[132:135], v[198:201], v[92:95]
	v_mfma_f32_16x16x32_bf16 v[88:91], v[152:155], v[198:201], v[88:91]
	s_waitcnt lgkmcnt(0)
	v_mfma_f32_16x16x32_bf16 v[76:79], v[132:135], v[206:209], v[76:79]
	v_mfma_f32_16x16x32_bf16 v[72:75], v[152:155], v[206:209], v[72:75]
	s_barrier
	s_add_i32 s98, 0, 0x1c000
	s_add_i32 s28, s88, s72
	s_add_i32 m0, s28, 0xffffff80
	ds_read_b128 v[210:213], v172 offset:49152
	ds_read_b128 v[214:217], v172 offset:50176
	ds_read_b128 v[232:235], v172 offset:51200
	ds_read_b128 v[236:239], v172 offset:52224
	global_load_lds_dwordx4 v138, s[68:69] offset:128
	s_add_i32 m0, s28, 0x1f80
	s_nop 0
	global_load_lds_dwordx4 v142, s[68:69] offset:128
	s_barrier
	s_waitcnt lgkmcnt(3)
	v_mfma_f32_16x16x32_bf16 v[116:119], v[210:213], v[156:159], v[116:119]
	s_waitcnt lgkmcnt(1)
	v_mfma_f32_16x16x32_bf16 v[112:115], v[232:235], v[156:159], v[112:115]
	v_mfma_f32_16x16x32_bf16 v[100:103], v[210:213], v[164:167], v[100:103]
	v_mfma_f32_16x16x32_bf16 v[96:99], v[232:235], v[164:167], v[96:99]
	v_mfma_f32_16x16x32_bf16 v[84:87], v[210:213], v[194:197], v[84:87]
	v_mfma_f32_16x16x32_bf16 v[80:83], v[232:235], v[194:197], v[80:83]
	v_mfma_f32_16x16x32_bf16 v[68:71], v[210:213], v[202:205], v[68:71]
	v_mfma_f32_16x16x32_bf16 v[64:67], v[232:235], v[202:205], v[64:67]
	v_mfma_f32_16x16x32_bf16 v[116:119], v[214:217], v[160:163], v[116:119]
	s_waitcnt lgkmcnt(0)
	v_mfma_f32_16x16x32_bf16 v[112:115], v[236:239], v[160:163], v[112:115]
	v_mfma_f32_16x16x32_bf16 v[100:103], v[214:217], v[168:171], v[100:103]
	v_mfma_f32_16x16x32_bf16 v[96:99], v[236:239], v[168:171], v[96:99]
	v_mfma_f32_16x16x32_bf16 v[84:87], v[214:217], v[198:201], v[84:87]
	v_mfma_f32_16x16x32_bf16 v[80:83], v[236:239], v[198:201], v[80:83]
	v_mfma_f32_16x16x32_bf16 v[68:71], v[214:217], v[206:209], v[68:71]
	v_mfma_f32_16x16x32_bf16 v[64:67], v[236:239], v[206:209], v[64:67]
	s_add_i32 m0, s79, 0xffffff80
	s_barrier
	ds_read_b128 v[156:159], v192 offset:49152
	ds_read_b128 v[164:167], v192 offset:51200
	ds_read_b128 v[194:197], v192 offset:53248
	ds_read_b128 v[202:205], v192 offset:55296
	ds_read_b128 v[160:163], v192 offset:50176
	ds_read_b128 v[168:171], v192 offset:52224
	ds_read_b128 v[198:201], v192 offset:54272
	ds_read_b128 v[206:209], v192 offset:56320
	global_load_lds_dwordx4 v136, s[70:71] offset:128
	s_add_i32 m0, s80, 0xffffff80
	s_nop 0
	global_load_lds_dwordx4 v140, s[70:71] offset:128
	s_barrier
	s_waitcnt lgkmcnt(7)
	v_mfma_f32_16x16x32_bf16 v[60:63], v[128:131], v[156:159], v[60:63]
	v_mfma_f32_16x16x32_bf16 v[56:59], v[148:151], v[156:159], v[56:59]
	s_waitcnt lgkmcnt(6)
	v_mfma_f32_16x16x32_bf16 v[44:47], v[128:131], v[164:167], v[44:47]
	v_mfma_f32_16x16x32_bf16 v[40:43], v[148:151], v[164:167], v[40:43]
	s_waitcnt lgkmcnt(5)
	v_mfma_f32_16x16x32_bf16 v[28:31], v[128:131], v[194:197], v[28:31]
	v_mfma_f32_16x16x32_bf16 v[24:27], v[148:151], v[194:197], v[24:27]
	s_waitcnt lgkmcnt(4)
	v_mfma_f32_16x16x32_bf16 v[12:15], v[128:131], v[202:205], v[12:15]
	v_mfma_f32_16x16x32_bf16 v[8:11], v[148:151], v[202:205], v[8:11]
	s_waitcnt lgkmcnt(3)
	v_mfma_f32_16x16x32_bf16 v[60:63], v[132:135], v[160:163], v[60:63]
	v_mfma_f32_16x16x32_bf16 v[56:59], v[152:155], v[160:163], v[56:59]
	s_waitcnt lgkmcnt(2)
	v_mfma_f32_16x16x32_bf16 v[44:47], v[132:135], v[168:171], v[44:47]
	v_mfma_f32_16x16x32_bf16 v[40:43], v[152:155], v[168:171], v[40:43]
	s_waitcnt lgkmcnt(1)
	v_mfma_f32_16x16x32_bf16 v[28:31], v[132:135], v[198:201], v[28:31]
	v_mfma_f32_16x16x32_bf16 v[24:27], v[152:155], v[198:201], v[24:27]
	s_waitcnt lgkmcnt(0)
	v_mfma_f32_16x16x32_bf16 v[12:15], v[132:135], v[206:209], v[12:15]
	v_mfma_f32_16x16x32_bf16 v[8:11], v[152:155], v[206:209], v[8:11]
	s_barrier
	s_add_u32 s28, s68, 0x40080
	s_addc_u32 s29, s69, 0
	s_add_i32 s68, s98, s72
	s_mov_b32 m0, s68
	s_nop 0
	global_load_lds_dwordx4 v138, s[28:29]
	s_add_i32 m0, s68, 0x2000
	s_nop 0
	global_load_lds_dwordx4 v142, s[28:29]
	s_waitcnt vmcnt(6)
	s_barrier
	v_mfma_f32_16x16x32_bf16 v[52:55], v[210:213], v[156:159], v[52:55]
	v_mfma_f32_16x16x32_bf16 v[48:51], v[232:235], v[156:159], v[48:51]
	v_mfma_f32_16x16x32_bf16 v[36:39], v[210:213], v[164:167], v[36:39]
	v_mfma_f32_16x16x32_bf16 v[32:35], v[232:235], v[164:167], v[32:35]
	v_mfma_f32_16x16x32_bf16 v[20:23], v[210:213], v[194:197], v[20:23]
	v_mfma_f32_16x16x32_bf16 v[16:19], v[232:235], v[194:197], v[16:19]
	v_mfma_f32_16x16x32_bf16 v[4:7], v[210:213], v[202:205], v[4:7]
	v_mfma_f32_16x16x32_bf16 v[0:3], v[232:235], v[202:205], v[0:3]
	v_mfma_f32_16x16x32_bf16 v[52:55], v[214:217], v[160:163], v[52:55]
	v_mfma_f32_16x16x32_bf16 v[48:51], v[236:239], v[160:163], v[48:51]
	v_mfma_f32_16x16x32_bf16 v[36:39], v[214:217], v[168:171], v[36:39]
	v_mfma_f32_16x16x32_bf16 v[32:35], v[236:239], v[168:171], v[32:35]
	v_mfma_f32_16x16x32_bf16 v[20:23], v[214:217], v[198:201], v[20:23]
	v_mfma_f32_16x16x32_bf16 v[16:19], v[236:239], v[198:201], v[16:19]
	v_mfma_f32_16x16x32_bf16 v[4:7], v[214:217], v[206:209], v[4:7]
	v_mfma_f32_16x16x32_bf16 v[0:3], v[236:239], v[206:209], v[0:3]
	s_add_i32 vcc_lo, vcc_lo, 2
	s_add_u32 s66, s66, 0x100
	s_addc_u32 s67, s67, 0
	s_add_u32 s85, s85, 0x100
	s_addc_u32 s91, s91, 0
	s_cmp_lt_u32 vcc_lo, 14
	s_barrier
	s_cbranch_scc1 .LBB0_134
	s_lshl_b32 s4, s4, 8
	v_mov_b32_e32 v176, v175
	v_mov_b32_e32 v188, v190
	s_add_i32 s4, s4, s77
	s_cmp_gt_i32 s6, 7
	v_add_u32_e32 v148, s4, v176
	v_lshlrev_b32_e32 v128, 2, v188
	v_ashrrev_i32_e32 v129, 31, v128
	v_ashrrev_i32_e32 v149, 31, v148
	v_lshl_add_u64 v[128:129], v[128:129], 2, s[8:9]
	v_lshlrev_b64 v[130:131], 6, v[148:149]
	v_add_u32_e32 v166, 16, v148
	v_lshl_add_u64 v[130:131], v[128:129], 0, v[130:131]
	v_ashrrev_i32_e32 v167, 31, v166
	global_load_dwordx4 v[160:163], v[130:131], off
	v_lshlrev_b64 v[130:131], 6, v[166:167]
	v_lshl_add_u64 v[130:131], v[128:129], 0, v[130:131]
	global_load_dwordx4 v[168:171], v[130:131], off
	v_add_u32_e32 v164, 32, v148
	v_ashrrev_i32_e32 v165, 31, v164
	v_lshlrev_b64 v[130:131], 6, v[164:165]
	v_add_u32_e32 v158, 48, v148
	v_lshl_add_u64 v[130:131], v[128:129], 0, v[130:131]
	v_ashrrev_i32_e32 v159, 31, v158
	global_load_dwordx4 v[194:197], v[130:131], off
	v_lshlrev_b64 v[130:131], 6, v[158:159]
	v_lshl_add_u64 v[130:131], v[128:129], 0, v[130:131]
	global_load_dwordx4 v[198:201], v[130:131], off
	v_add_u32_e32 v156, 0x80, v148
	v_ashrrev_i32_e32 v157, 31, v156
	v_lshlrev_b64 v[130:131], 6, v[156:157]
	v_add_u32_e32 v154, 0x90, v148
	v_lshl_add_u64 v[130:131], v[128:129], 0, v[130:131]
	v_ashrrev_i32_e32 v155, 31, v154
	global_load_dwordx4 v[202:205], v[130:131], off
	v_lshlrev_b64 v[130:131], 6, v[154:155]
	v_add_u32_e32 v152, 0xa0, v148
	v_lshl_add_u64 v[130:131], v[128:129], 0, v[130:131]
	v_ashrrev_i32_e32 v153, 31, v152
	global_load_dwordx4 v[206:209], v[130:131], off
	v_lshlrev_b64 v[130:131], 6, v[152:153]
	v_add_u32_e32 v150, 0xb0, v148
	v_lshl_add_u64 v[130:131], v[128:129], 0, v[130:131]
	v_ashrrev_i32_e32 v151, 31, v150
	global_load_dwordx4 v[132:135], v[130:131], off
	v_lshlrev_b64 v[130:131], 6, v[150:151]
	v_lshl_add_u64 v[128:129], v[128:129], 0, v[130:131]
	global_load_dwordx4 v[128:131], v[128:129], off
	s_cselect_b64 s[66:67], -1, 0
	s_lshl_b32 s7, s6, 8
	s_add_i32 s7, s81, s7
	s_cmp_lt_i32 s6, 8
	s_mov_b64 s[68:69], -1
	s_waitcnt vmcnt(0)
	v_mov_b32_e32 v172, v161
	v_mov_b32_e32 v173, v162
	v_mov_b32_e32 v161, v163
	v_mov_b32_e32 v162, v169
	v_mov_b32_e32 v163, v170
	v_mov_b32_e32 v169, v171
	v_pk_add_f32 v[160:161], v[172:173], v[160:161]
	v_pk_add_f32 v[162:163], v[162:163], v[168:169]
	v_mov_b32_e32 v169, v160
	v_mov_b32_e32 v168, v162
	v_mov_b32_e32 v160, v163
	v_pk_add_f32 v[160:161], v[168:169], v[160:161]
	v_mov_b32_e32 v163, v161
	v_mov_b32_e32 v162, v160
	s_waitcnt lgkmcnt(0)
	s_nop 0
	v_permlane16_swap_b32 v161, v163
	v_permlane16_swap_b32 v160, v162
	v_pk_add_f32 v[160:161], v[160:161], v[162:163]
	v_mov_b32_e32 v163, v161
	v_mov_b32_e32 v162, v160
	s_waitcnt lgkmcnt(0)
	s_nop 0
	v_permlane32_swap_b32 v161, v163
	v_permlane32_swap_b32 v160, v162
	v_pk_add_f32 v[160:161], v[160:161], v[162:163]
	s_nop 0
	v_pk_fma_f32 v[172:173], v[160:161], s[30:31], v[178:179] op_sel_hi:[1,0,0]
	v_mov_b32_e32 v162, v199
	v_mul_f32_e32 v160, 0x4b800000, v173
	v_cmp_gt_f32_e32 vcc, s86, v173
	v_mov_b32_e32 v163, v200
	v_mov_b32_e32 v199, v201
	v_cndmask_b32_e32 v160, v173, v160, vcc
	v_rsq_f32_e32 v160, v160
	v_pk_add_f32 v[162:163], v[162:163], v[198:199]
	v_cmp_gt_f32_e64 s[4:5], s86, v172
	v_mov_b32_e32 v168, v162
	v_mul_f32_e32 v161, 0x45800000, v160
	v_cndmask_b32_e32 v174, v160, v161, vcc
	v_mov_b32_e32 v160, v195
	v_mov_b32_e32 v161, v196
	v_mov_b32_e32 v195, v197
	v_pk_add_f32 v[160:161], v[160:161], v[194:195]
	s_nop 0
	v_mov_b32_e32 v169, v160
	v_mov_b32_e32 v160, v163
	v_pk_add_f32 v[160:161], v[168:169], v[160:161]
	v_mov_b32_e32 v163, v161
	v_mov_b32_e32 v162, v160
	s_waitcnt lgkmcnt(0)
	s_nop 0
	v_permlane16_swap_b32 v161, v163
	v_permlane16_swap_b32 v160, v162
	v_pk_add_f32 v[168:169], v[160:161], v[162:163]
	v_mov_b32_e32 v160, v203
	v_mov_b32_e32 v161, v204
	v_mov_b32_e32 v203, v205
	v_mov_b32_e32 v162, v207
	v_mov_b32_e32 v163, v208
	v_mov_b32_e32 v207, v209
	v_pk_add_f32 v[160:161], v[160:161], v[202:203]
	v_pk_add_f32 v[162:163], v[162:163], v[206:207]
	v_mov_b32_e32 v195, v160
	v_mov_b32_e32 v194, v162
	v_mov_b32_e32 v160, v163
	v_pk_add_f32 v[160:161], v[194:195], v[160:161]
	v_mov_b32_e32 v194, v133
	v_mov_b32_e32 v195, v134
	v_mov_b32_e32 v133, v135
	v_mov_b32_e32 v134, v129
	v_mov_b32_e32 v135, v130
	v_mov_b32_e32 v129, v131
	v_pk_add_f32 v[132:133], v[194:195], v[132:133]
	v_pk_add_f32 v[128:129], v[134:135], v[128:129]
	v_mov_b32_e32 v131, v132
	v_mov_b32_e32 v130, v128
	v_mov_b32_e32 v132, v129
	v_pk_add_f32 v[128:129], v[130:131], v[132:133]
	v_mov_b32_e32 v163, v161
	v_mov_b32_e32 v162, v160
	ds_bpermute_b32 v131, v219, v129
	v_mov_b32_e32 v130, v128
	ds_bpermute_b32 v171, v218, v169
	ds_bpermute_b32 v170, v218, v168
	s_waitcnt lgkmcnt(3)
	v_permlane16_swap_b32 v161, v163
	v_permlane16_swap_b32 v160, v162
	v_pk_add_f32 v[160:161], v[160:161], v[162:163]
	ds_bpermute_b32 v163, v218, v161
	s_waitcnt lgkmcnt(3)
	v_permlane16_swap_b32 v128, v130
	v_pk_add_f32 v[132:133], v[128:129], v[130:131]
	ds_bpermute_b32 v162, v218, v160
	ds_bpermute_b32 v135, v218, v133
	ds_bpermute_b32 v134, v218, v132
	v_lshlrev_b32_e32 v128, 3, v188
	v_add_u32_e32 v130, s7, v128
	v_lshlrev_b64 v[188:189], 11, v[148:149]
	v_ashrrev_i32_e32 v131, 31, v130
	s_cbranch_scc1 .LBB0_137
	v_mul_f32_e32 v196, v120, v174
	v_mul_f32_e32 v197, v121, v174
	v_mul_f32_e32 v198, v122, v174
	v_mul_f32_e32 v199, v123, v174
	v_mul_f32_e32 v129, v124, v174
	v_mul_f32_e32 v149, v125, v174
	v_mul_f32_e32 v173, v126, v174
	v_mul_f32_e32 v193, v127, v174
	v_cvt_pk_bf16_f32 v194, v129, v149
	v_cvt_pk_bf16_f32 v195, v173, v193
	v_cvt_pk_bf16_f32 v196, v196, v197
	v_cvt_pk_bf16_f32 v197, v198, v199
	v_lshl_add_u64 v[198:199], s[12:13], 0, v[188:189]
	v_lshl_add_u64 v[198:199], v[130:131], 1, v[198:199]
	global_store_dwordx4 v[198:199], v[194:197], off
	s_mov_b64 s[68:69], 0
	v_mul_f32_e32 v129, v116, v174
	v_mul_f32_e32 v196, v112, v174
	v_mul_f32_e32 v197, v113, v174
	v_mul_f32_e32 v149, v117, v174
	v_mul_f32_e32 v173, v118, v174
	v_mul_f32_e32 v193, v119, v174
	v_mul_f32_e32 v200, v114, v174
	v_mul_f32_e32 v201, v115, v174
	v_cvt_pk_bf16_f32 v194, v129, v149
	v_cvt_pk_bf16_f32 v195, v173, v193
	v_cvt_pk_bf16_f32 v196, v196, v197
	v_cvt_pk_bf16_f32 v197, v200, v201
	global_store_dwordx4 v[198:199], v[194:197], off offset:256

.LBB0_1114:
	s_add_i32 vcc_hi, s66, 2
	s_add_u32 s28, s64, 0x80
	s_addc_u32 s29, s65, 0
	s_add_i32 s88, 0, 0x10000
	ds_read_b128 v[128:131], v174
	ds_read_b128 v[132:135], v174 offset:1024
	ds_read_b128 v[136:139], v174 offset:2048
	ds_read_b128 v[140:143], v174 offset:3072
	s_cmp_eq_u32 s85, s66
	s_cselect_b32 s66, s4, s28
	s_cselect_b32 s67, s5, s29
	s_cselect_b32 s69, s7, vcc_lo
	s_cselect_b32 s68, s6, s91
	s_add_i32 m0, s70, 0xc000
	ds_read_b128 v[144:147], v195
	ds_read_b128 v[162:165], v195 offset:2048
	ds_read_b128 v[170:173], v195 offset:4096
	ds_read_b128 v[196:199], v195 offset:6144
	ds_read_b128 v[148:151], v195 offset:1024
	ds_read_b128 v[166:169], v195 offset:3072
	ds_read_b128 v[188:191], v195 offset:5120
	ds_read_b128 v[200:203], v195 offset:7168
	global_load_lds_dwordx4 v158, s[64:65]
	s_add_i32 m0, s70, 0xe000
	s_nop 0
	global_load_lds_dwordx4 v160, s[64:65]
	s_waitcnt lgkmcnt(8)
	s_barrier
	s_waitcnt lgkmcnt(7)
	v_mfma_f32_16x16x32_bf16 v[124:127], v[128:131], v[144:147], v[124:127]
	v_mfma_f32_16x16x32_bf16 v[120:123], v[136:139], v[144:147], v[120:123]
	s_waitcnt lgkmcnt(6)
	v_mfma_f32_16x16x32_bf16 v[108:111], v[128:131], v[162:165], v[108:111]
	v_mfma_f32_16x16x32_bf16 v[104:107], v[136:139], v[162:165], v[104:107]
	s_waitcnt lgkmcnt(5)
	v_mfma_f32_16x16x32_bf16 v[92:95], v[128:131], v[170:173], v[92:95]
	v_mfma_f32_16x16x32_bf16 v[88:91], v[136:139], v[170:173], v[88:91]
	s_waitcnt lgkmcnt(4)
	v_mfma_f32_16x16x32_bf16 v[76:79], v[128:131], v[196:199], v[76:79]
	v_mfma_f32_16x16x32_bf16 v[72:75], v[136:139], v[196:199], v[72:75]
	s_waitcnt lgkmcnt(3)
	v_mfma_f32_16x16x32_bf16 v[124:127], v[132:135], v[148:151], v[124:127]
	v_mfma_f32_16x16x32_bf16 v[120:123], v[140:143], v[148:151], v[120:123]
	s_waitcnt lgkmcnt(2)
	v_mfma_f32_16x16x32_bf16 v[108:111], v[132:135], v[166:169], v[108:111]
	v_mfma_f32_16x16x32_bf16 v[104:107], v[140:143], v[166:169], v[104:107]
	s_waitcnt lgkmcnt(1)
	v_mfma_f32_16x16x32_bf16 v[92:95], v[132:135], v[188:191], v[92:95]
	v_mfma_f32_16x16x32_bf16 v[88:91], v[140:143], v[188:191], v[88:91]
	s_waitcnt lgkmcnt(0)
	v_mfma_f32_16x16x32_bf16 v[76:79], v[132:135], v[200:203], v[76:79]
	v_mfma_f32_16x16x32_bf16 v[72:75], v[140:143], v[200:203], v[72:75]
	s_barrier
	s_add_i32 s28, 0, 0x14000
	s_add_i32 s29, s88, s47
	ds_read_b128 v[204:207], v174 offset:16384
	ds_read_b128 v[208:211], v174 offset:17408
	ds_read_b128 v[212:215], v174 offset:18432
	ds_read_b128 v[232:235], v174 offset:19456
	s_mov_b32 m0, s29
	s_nop 0
	global_load_lds_dwordx4 v176, s[68:69]
	s_add_i32 m0, s29, 0x2000
	s_nop 0
	global_load_lds_dwordx4 v156, s[68:69]
	s_barrier
	s_waitcnt lgkmcnt(3)
	v_mfma_f32_16x16x32_bf16 v[116:119], v[204:207], v[144:147], v[116:119]
	s_waitcnt lgkmcnt(1)
	v_mfma_f32_16x16x32_bf16 v[112:115], v[212:215], v[144:147], v[112:115]
	v_mfma_f32_16x16x32_bf16 v[100:103], v[204:207], v[162:165], v[100:103]
	v_mfma_f32_16x16x32_bf16 v[96:99], v[212:215], v[162:165], v[96:99]
	v_mfma_f32_16x16x32_bf16 v[84:87], v[204:207], v[170:173], v[84:87]
	v_mfma_f32_16x16x32_bf16 v[80:83], v[212:215], v[170:173], v[80:83]
	v_mfma_f32_16x16x32_bf16 v[68:71], v[204:207], v[196:199], v[68:71]
	v_mfma_f32_16x16x32_bf16 v[64:67], v[212:215], v[196:199], v[64:67]
	v_mfma_f32_16x16x32_bf16 v[116:119], v[208:211], v[148:151], v[116:119]
	s_waitcnt lgkmcnt(0)
	v_mfma_f32_16x16x32_bf16 v[112:115], v[232:235], v[148:151], v[112:115]
	v_mfma_f32_16x16x32_bf16 v[100:103], v[208:211], v[166:169], v[100:103]
	v_mfma_f32_16x16x32_bf16 v[96:99], v[232:235], v[166:169], v[96:99]
	v_mfma_f32_16x16x32_bf16 v[84:87], v[208:211], v[188:191], v[84:87]
	v_mfma_f32_16x16x32_bf16 v[80:83], v[232:235], v[188:191], v[80:83]
	v_mfma_f32_16x16x32_bf16 v[68:71], v[208:211], v[200:203], v[68:71]
	v_mfma_f32_16x16x32_bf16 v[64:67], v[232:235], v[200:203], v[64:67]
	s_mov_b32 m0, s70
	s_barrier
	ds_read_b128 v[144:147], v195 offset:16384
	ds_read_b128 v[162:165], v195 offset:18432
	ds_read_b128 v[170:173], v195 offset:20480
	ds_read_b128 v[196:199], v195 offset:22528
	ds_read_b128 v[148:151], v195 offset:17408
	ds_read_b128 v[166:169], v195 offset:19456
	ds_read_b128 v[188:191], v195 offset:21504
	ds_read_b128 v[200:203], v195 offset:23552
	global_load_lds_dwordx4 v152, s[66:67]
	s_mov_b32 m0, s71
	s_nop 0
	global_load_lds_dwordx4 v154, s[66:67]
	s_barrier
	s_waitcnt lgkmcnt(7)
	v_mfma_f32_16x16x32_bf16 v[60:63], v[128:131], v[144:147], v[60:63]
	v_mfma_f32_16x16x32_bf16 v[56:59], v[136:139], v[144:147], v[56:59]
	s_waitcnt lgkmcnt(6)
	v_mfma_f32_16x16x32_bf16 v[44:47], v[128:131], v[162:165], v[44:47]
	v_mfma_f32_16x16x32_bf16 v[40:43], v[136:139], v[162:165], v[40:43]
	s_waitcnt lgkmcnt(5)
	v_mfma_f32_16x16x32_bf16 v[28:31], v[128:131], v[170:173], v[28:31]
	v_mfma_f32_16x16x32_bf16 v[24:27], v[136:139], v[170:173], v[24:27]
	s_waitcnt lgkmcnt(4)
	v_mfma_f32_16x16x32_bf16 v[12:15], v[128:131], v[196:199], v[12:15]
	v_mfma_f32_16x16x32_bf16 v[8:11], v[136:139], v[196:199], v[8:11]
	s_waitcnt lgkmcnt(3)
	v_mfma_f32_16x16x32_bf16 v[60:63], v[132:135], v[148:151], v[60:63]
	v_mfma_f32_16x16x32_bf16 v[56:59], v[140:143], v[148:151], v[56:59]
	s_waitcnt lgkmcnt(2)
	v_mfma_f32_16x16x32_bf16 v[44:47], v[132:135], v[166:169], v[44:47]
	v_mfma_f32_16x16x32_bf16 v[40:43], v[140:143], v[166:169], v[40:43]
	s_waitcnt lgkmcnt(1)
	v_mfma_f32_16x16x32_bf16 v[28:31], v[132:135], v[188:191], v[28:31]
	v_mfma_f32_16x16x32_bf16 v[24:27], v[140:143], v[188:191], v[24:27]
	s_waitcnt lgkmcnt(0)
	v_mfma_f32_16x16x32_bf16 v[12:15], v[132:135], v[200:203], v[12:15]
	v_mfma_f32_16x16x32_bf16 v[8:11], v[140:143], v[200:203], v[8:11]
	s_barrier
	s_add_u32 s98, s68, s58
	s_addc_u32 s99, s69, 0
	s_add_i32 s28, s28, s47
	s_mov_b32 m0, s28
	s_nop 0
	global_load_lds_dwordx4 v176, s[98:99]
	s_add_i32 m0, s28, 0x2000
	s_nop 0
	global_load_lds_dwordx4 v156, s[98:99]
	s_waitcnt vmcnt(6)
	s_barrier
	v_mfma_f32_16x16x32_bf16 v[52:55], v[204:207], v[144:147], v[52:55]
	v_mfma_f32_16x16x32_bf16 v[48:51], v[212:215], v[144:147], v[48:51]
	v_mfma_f32_16x16x32_bf16 v[36:39], v[204:207], v[162:165], v[36:39]
	v_mfma_f32_16x16x32_bf16 v[32:35], v[212:215], v[162:165], v[32:35]
	v_mfma_f32_16x16x32_bf16 v[20:23], v[204:207], v[170:173], v[20:23]
	v_mfma_f32_16x16x32_bf16 v[16:19], v[212:215], v[170:173], v[16:19]
	v_mfma_f32_16x16x32_bf16 v[4:7], v[204:207], v[196:199], v[4:7]
	v_mfma_f32_16x16x32_bf16 v[0:3], v[212:215], v[196:199], v[0:3]
	v_mfma_f32_16x16x32_bf16 v[52:55], v[208:211], v[148:151], v[52:55]
	v_mfma_f32_16x16x32_bf16 v[48:51], v[232:235], v[148:151], v[48:51]
	v_mfma_f32_16x16x32_bf16 v[36:39], v[208:211], v[166:169], v[36:39]
	v_mfma_f32_16x16x32_bf16 v[32:35], v[232:235], v[166:169], v[32:35]
	v_mfma_f32_16x16x32_bf16 v[20:23], v[208:211], v[188:191], v[20:23]
	v_mfma_f32_16x16x32_bf16 v[16:19], v[232:235], v[188:191], v[16:19]
	v_mfma_f32_16x16x32_bf16 v[4:7], v[208:211], v[200:203], v[4:7]
	v_mfma_f32_16x16x32_bf16 v[0:3], v[232:235], v[200:203], v[0:3]
	s_add_i32 s28, 0, 0x18000
	s_barrier
	ds_read_b128 v[128:131], v174 offset:32768
	ds_read_b128 v[132:135], v174 offset:33792
	ds_read_b128 v[136:139], v174 offset:34816
	ds_read_b128 v[140:143], v174 offset:35840
	s_add_u32 s100, s66, s58
	s_addc_u32 s101, s67, 0
	s_mov_b32 m0, s72
	ds_read_b128 v[144:147], v195 offset:32768
	ds_read_b128 v[162:165], v195 offset:34816
	ds_read_b128 v[170:173], v195 offset:36864
	ds_read_b128 v[196:199], v195 offset:38912
	ds_read_b128 v[148:151], v195 offset:33792
	ds_read_b128 v[166:169], v195 offset:35840
	ds_read_b128 v[188:191], v195 offset:37888
	ds_read_b128 v[200:203], v195 offset:39936
	global_load_lds_dwordx4 v152, s[100:101]
	s_mov_b32 m0, s73
	s_nop 0
	global_load_lds_dwordx4 v154, s[100:101]
	s_waitcnt lgkmcnt(8)
	s_barrier
	s_waitcnt lgkmcnt(7)
	v_mfma_f32_16x16x32_bf16 v[124:127], v[128:131], v[144:147], v[124:127]
	v_mfma_f32_16x16x32_bf16 v[120:123], v[136:139], v[144:147], v[120:123]
	s_waitcnt lgkmcnt(6)
	v_mfma_f32_16x16x32_bf16 v[108:111], v[128:131], v[162:165], v[108:111]
	v_mfma_f32_16x16x32_bf16 v[104:107], v[136:139], v[162:165], v[104:107]
	s_waitcnt lgkmcnt(5)
	v_mfma_f32_16x16x32_bf16 v[92:95], v[128:131], v[170:173], v[92:95]
	v_mfma_f32_16x16x32_bf16 v[88:91], v[136:139], v[170:173], v[88:91]
	s_waitcnt lgkmcnt(4)
	v_mfma_f32_16x16x32_bf16 v[76:79], v[128:131], v[196:199], v[76:79]
	v_mfma_f32_16x16x32_bf16 v[72:75], v[136:139], v[196:199], v[72:75]
	s_waitcnt lgkmcnt(3)
	v_mfma_f32_16x16x32_bf16 v[124:127], v[132:135], v[148:151], v[124:127]
	v_mfma_f32_16x16x32_bf16 v[120:123], v[140:143], v[148:151], v[120:123]
	s_waitcnt lgkmcnt(2)
	v_mfma_f32_16x16x32_bf16 v[108:111], v[132:135], v[166:169], v[108:111]
	v_mfma_f32_16x16x32_bf16 v[104:107], v[140:143], v[166:169], v[104:107]
	s_waitcnt lgkmcnt(1)
	v_mfma_f32_16x16x32_bf16 v[92:95], v[132:135], v[188:191], v[92:95]
	v_mfma_f32_16x16x32_bf16 v[88:91], v[140:143], v[188:191], v[88:91]
	s_waitcnt lgkmcnt(0)
	v_mfma_f32_16x16x32_bf16 v[76:79], v[132:135], v[200:203], v[76:79]
	v_mfma_f32_16x16x32_bf16 v[72:75], v[140:143], v[200:203], v[72:75]
	s_barrier
	s_add_i32 s29, 0, 0x1c000
	s_add_i32 s28, s28, s47
	s_add_i32 m0, s28, 0xffffff80
	ds_read_b128 v[204:207], v174 offset:49152
	ds_read_b128 v[208:211], v174 offset:50176
	ds_read_b128 v[212:215], v174 offset:51200
	ds_read_b128 v[232:235], v174 offset:52224
	global_load_lds_dwordx4 v176, s[68:69] offset:128
	s_add_i32 m0, s28, 0x1f80
	s_nop 0
	global_load_lds_dwordx4 v156, s[68:69] offset:128
	s_barrier
	s_waitcnt lgkmcnt(3)
	v_mfma_f32_16x16x32_bf16 v[116:119], v[204:207], v[144:147], v[116:119]
	s_waitcnt lgkmcnt(1)
	v_mfma_f32_16x16x32_bf16 v[112:115], v[212:215], v[144:147], v[112:115]
	v_mfma_f32_16x16x32_bf16 v[100:103], v[204:207], v[162:165], v[100:103]
	v_mfma_f32_16x16x32_bf16 v[96:99], v[212:215], v[162:165], v[96:99]
	v_mfma_f32_16x16x32_bf16 v[84:87], v[204:207], v[170:173], v[84:87]
	v_mfma_f32_16x16x32_bf16 v[80:83], v[212:215], v[170:173], v[80:83]
	v_mfma_f32_16x16x32_bf16 v[68:71], v[204:207], v[196:199], v[68:71]
	v_mfma_f32_16x16x32_bf16 v[64:67], v[212:215], v[196:199], v[64:67]
	v_mfma_f32_16x16x32_bf16 v[116:119], v[208:211], v[148:151], v[116:119]
	s_waitcnt lgkmcnt(0)
	v_mfma_f32_16x16x32_bf16 v[112:115], v[232:235], v[148:151], v[112:115]
	v_mfma_f32_16x16x32_bf16 v[100:103], v[208:211], v[166:169], v[100:103]
	v_mfma_f32_16x16x32_bf16 v[96:99], v[232:235], v[166:169], v[96:99]
	v_mfma_f32_16x16x32_bf16 v[84:87], v[208:211], v[188:191], v[84:87]
	v_mfma_f32_16x16x32_bf16 v[80:83], v[232:235], v[188:191], v[80:83]
	v_mfma_f32_16x16x32_bf16 v[68:71], v[208:211], v[200:203], v[68:71]
	v_mfma_f32_16x16x32_bf16 v[64:67], v[232:235], v[200:203], v[64:67]
	s_add_i32 m0, s74, 0xffffff80
	s_barrier
	ds_read_b128 v[144:147], v195 offset:49152
	ds_read_b128 v[162:165], v195 offset:51200
	ds_read_b128 v[170:173], v195 offset:53248
	ds_read_b128 v[196:199], v195 offset:55296
	ds_read_b128 v[148:151], v195 offset:50176
	ds_read_b128 v[166:169], v195 offset:52224
	ds_read_b128 v[188:191], v195 offset:54272
	ds_read_b128 v[200:203], v195 offset:56320
	global_load_lds_dwordx4 v152, s[66:67] offset:128
	s_add_i32 m0, s75, 0xffffff80
	s_nop 0
	global_load_lds_dwordx4 v154, s[66:67] offset:128
	s_barrier
	s_waitcnt lgkmcnt(7)
	v_mfma_f32_16x16x32_bf16 v[60:63], v[128:131], v[144:147], v[60:63]
	v_mfma_f32_16x16x32_bf16 v[56:59], v[136:139], v[144:147], v[56:59]
	s_waitcnt lgkmcnt(6)
	v_mfma_f32_16x16x32_bf16 v[44:47], v[128:131], v[162:165], v[44:47]
	v_mfma_f32_16x16x32_bf16 v[40:43], v[136:139], v[162:165], v[40:43]
	s_waitcnt lgkmcnt(5)
	v_mfma_f32_16x16x32_bf16 v[28:31], v[128:131], v[170:173], v[28:31]
	v_mfma_f32_16x16x32_bf16 v[24:27], v[136:139], v[170:173], v[24:27]
	s_waitcnt lgkmcnt(4)
	v_mfma_f32_16x16x32_bf16 v[12:15], v[128:131], v[196:199], v[12:15]
	v_mfma_f32_16x16x32_bf16 v[8:11], v[136:139], v[196:199], v[8:11]
	s_waitcnt lgkmcnt(3)
	v_mfma_f32_16x16x32_bf16 v[60:63], v[132:135], v[148:151], v[60:63]
	v_mfma_f32_16x16x32_bf16 v[56:59], v[140:143], v[148:151], v[56:59]
	s_waitcnt lgkmcnt(2)
	v_mfma_f32_16x16x32_bf16 v[44:47], v[132:135], v[166:169], v[44:47]
	v_mfma_f32_16x16x32_bf16 v[40:43], v[140:143], v[166:169], v[40:43]
	s_waitcnt lgkmcnt(1)
	v_mfma_f32_16x16x32_bf16 v[28:31], v[132:135], v[188:191], v[28:31]
	v_mfma_f32_16x16x32_bf16 v[24:27], v[140:143], v[188:191], v[24:27]
	s_waitcnt lgkmcnt(0)
	v_mfma_f32_16x16x32_bf16 v[12:15], v[132:135], v[200:203], v[12:15]
	v_mfma_f32_16x16x32_bf16 v[8:11], v[140:143], v[200:203], v[8:11]
	s_barrier
	s_add_i32 s28, s29, s47
	s_add_i32 m0, s28, 0xffffff80
	s_nop 0
	global_load_lds_dwordx4 v176, s[98:99] offset:128
	s_add_i32 m0, s28, 0x1f80
	s_nop 0
	global_load_lds_dwordx4 v156, s[98:99] offset:128
	s_waitcnt vmcnt(6)
	s_barrier
	v_mfma_f32_16x16x32_bf16 v[52:55], v[204:207], v[144:147], v[52:55]
	v_mfma_f32_16x16x32_bf16 v[48:51], v[212:215], v[144:147], v[48:51]
	v_mfma_f32_16x16x32_bf16 v[36:39], v[204:207], v[162:165], v[36:39]
	v_mfma_f32_16x16x32_bf16 v[32:35], v[212:215], v[162:165], v[32:35]
	v_mfma_f32_16x16x32_bf16 v[20:23], v[204:207], v[170:173], v[20:23]
	v_mfma_f32_16x16x32_bf16 v[16:19], v[212:215], v[170:173], v[16:19]
	v_mfma_f32_16x16x32_bf16 v[4:7], v[204:207], v[196:199], v[4:7]
	v_mfma_f32_16x16x32_bf16 v[0:3], v[212:215], v[196:199], v[0:3]
	v_mfma_f32_16x16x32_bf16 v[52:55], v[208:211], v[148:151], v[52:55]
	v_mfma_f32_16x16x32_bf16 v[48:51], v[232:235], v[148:151], v[48:51]
	v_mfma_f32_16x16x32_bf16 v[36:39], v[208:211], v[166:169], v[36:39]
	v_mfma_f32_16x16x32_bf16 v[32:35], v[232:235], v[166:169], v[32:35]
	v_mfma_f32_16x16x32_bf16 v[20:23], v[208:211], v[188:191], v[20:23]
	v_mfma_f32_16x16x32_bf16 v[16:19], v[232:235], v[188:191], v[16:19]
	v_mfma_f32_16x16x32_bf16 v[4:7], v[208:211], v[200:203], v[4:7]
	v_mfma_f32_16x16x32_bf16 v[0:3], v[232:235], v[200:203], v[0:3]
	s_add_u32 s64, s64, 0x100
	s_addc_u32 s65, s65, 0
	s_add_u32 s91, s91, 0x100
	s_addc_u32 vcc_lo, vcc_lo, 0
	s_cmp_lt_i32 vcc_hi, s76
	s_mov_b32 s66, vcc_hi
	s_barrier
	s_cbranch_scc1 .LBB0_1114
	s_lshl_b32 s28, s84, 8
	v_mov_b32_e32 v128, v193
	v_mov_b32_e32 v129, v192
	s_add_i32 s28, s28, s78
	s_lshl_b32 s64, s24, 2
	v_add_u32_e32 v166, s28, v129
	s_lshl_b32 s28, s24, 8
	s_or_b32 s28, s28, s79
	v_lshl_add_u32 v162, v128, 3, s28
	v_ashrrev_i32_e32 v163, 31, v162
	v_lshlrev_b64 v[204:205], 1, v[162:163]
	v_ashrrev_i32_e32 v167, 31, v166
	v_lshl_add_u64 v[164:165], s[12:13], 0, v[204:205]
	v_lshlrev_b64 v[206:207], 11, v[166:167]
	v_cmp_eq_u32_e32 vcc, 0, v128
	v_lshl_add_u64 v[128:129], v[164:165], 0, v[206:207]
	global_load_dwordx4 v[196:199], v[128:129], off
	global_load_dwordx4 v[200:203], v[128:129], off offset:256
	v_add_u32_e32 v188, 16, v166
	v_ashrrev_i32_e32 v189, 31, v188
	v_add_u32_e32 v172, 32, v166
	v_lshlrev_b64 v[190:191], 11, v[188:189]
	v_ashrrev_i32_e32 v173, 31, v172
	v_add_u32_e32 v168, 48, v166
	v_lshl_add_u64 v[128:129], v[164:165], 0, v[190:191]
	v_lshlrev_b64 v[174:175], 11, v[172:173]
	v_ashrrev_i32_e32 v169, 31, v168
	global_load_dwordx4 v[148:151], v[128:129], off
	global_load_dwordx4 v[144:147], v[128:129], off offset:256
	v_lshl_add_u64 v[128:129], v[164:165], 0, v[174:175]
	v_lshlrev_b64 v[170:171], 11, v[168:169]
	global_load_dwordx4 v[140:143], v[128:129], off
	global_load_dwordx4 v[136:139], v[128:129], off offset:256
	v_lshl_add_u64 v[128:129], v[164:165], 0, v[170:171]
	global_load_dwordx4 v[132:135], v[128:129], off
	s_nop 0
	global_load_dwordx4 v[128:131], v[128:129], off offset:256
	v_lshl_add_u64 v[206:207], s[12:13], 0, v[206:207]
	v_lshl_add_u64 v[204:205], v[206:207], 0, v[204:205]
	s_ashr_i32 s65, s64, 31
	s_waitcnt vmcnt(0)
	v_lshlrev_b32_e32 v208, 16, v196
	v_and_b32_e32 v209, 0xffff0000, v196
	v_lshlrev_b32_e32 v196, 16, v197
	v_and_b32_e32 v197, 0xffff0000, v197
	v_lshlrev_b32_e32 v210, 16, v198
	v_and_b32_e32 v211, 0xffff0000, v198
	v_lshlrev_b32_e32 v198, 16, v199
	v_and_b32_e32 v199, 0xffff0000, v199
	v_pk_fma_f32 v[126:127], s[62:63], v[126:127], v[196:197]
	v_pk_fma_f32 v[124:125], s[10:11], v[124:125], v[208:209]
	v_pk_fma_f32 v[196:197], s[62:63], v[122:123], v[198:199]
	v_pk_fma_f32 v[198:199], s[10:11], v[120:121], v[210:211]
	v_cvt_pk_bf16_f32 v120, v124, v125
	v_cvt_pk_bf16_f32 v121, v126, v127
	s_nop 0
	v_cvt_pk_bf16_f32 v122, v198, v199
	v_cvt_pk_bf16_f32 v123, v196, v197
	global_store_dwordx4 v[204:205], v[120:123], off
	s_nop 1
	v_pk_mul_f32 v[120:121], v[198:199], v[198:199]
	v_pk_mul_f32 v[122:123], v[196:197], v[196:197]
	v_pk_fma_f32 v[120:121], v[124:125], v[124:125], v[120:121]
	v_pk_fma_f32 v[122:123], v[126:127], v[126:127], v[122:123]
	v_add_f32_e32 v120, v120, v121
	v_add_f32_e32 v121, v122, v123
	v_add_f32_e32 v196, v120, v121
	v_lshlrev_b32_e32 v120, 16, v200
	v_and_b32_e32 v121, 0xffff0000, v200
	v_lshlrev_b32_e32 v122, 16, v201
	v_and_b32_e32 v123, 0xffff0000, v201
	v_lshlrev_b32_e32 v124, 16, v202
	v_and_b32_e32 v125, 0xffff0000, v202
	v_lshlrev_b32_e32 v126, 16, v203
	v_and_b32_e32 v127, 0xffff0000, v203
	v_pk_fma_f32 v[118:119], s[62:63], v[118:119], v[122:123]
	v_pk_fma_f32 v[116:117], s[10:11], v[116:117], v[120:121]
	v_pk_fma_f32 v[120:121], s[62:63], v[114:115], v[126:127]
	v_pk_fma_f32 v[122:123], s[10:11], v[112:113], v[124:125]
	v_cvt_pk_bf16_f32 v112, v116, v117
	v_cvt_pk_bf16_f32 v113, v118, v119
	s_nop 0
	v_cvt_pk_bf16_f32 v114, v122, v123
	v_cvt_pk_bf16_f32 v115, v120, v121
	global_store_dwordx4 v[204:205], v[112:115], off offset:256
	s_nop 1
	v_pk_mul_f32 v[112:113], v[122:123], v[122:123]
	v_pk_mul_f32 v[114:115], v[120:121], v[120:121]
	v_pk_fma_f32 v[112:113], v[116:117], v[116:117], v[112:113]
	v_pk_fma_f32 v[114:115], v[118:119], v[118:119], v[114:115]
	v_add_f32_e32 v112, v112, v113
	v_add_f32_e32 v113, v114, v115
	v_add_f32_e32 v112, v112, v113
	v_add_f32_e32 v112, v196, v112
	v_mov_b32_e32 v113, v112
	s_waitcnt lgkmcnt(0)
	s_nop 0
	v_permlane16_swap_b32 v112, v113
	v_add_f32_e32 v112, v112, v113
	v_mov_b32_e32 v113, v112
	s_nop 1
	v_permlane32_swap_b32 v112, v113
	s_and_saveexec_b64 s[66:67], vcc
	s_cbranch_execz .LBB0_1117
	v_lshlrev_b64 v[114:115], 6, v[166:167]
	v_lshl_add_u64 v[114:115], s[8:9], 0, v[114:115]
	v_lshl_add_u64 v[114:115], s[64:65], 2, v[114:115]
	s_lshl_b32 s24, s77, 2
	v_lshl_add_u64 v[114:115], v[114:115], 0, s[24:25]
	s_waitcnt lgkmcnt(0)
	v_add_f32_e32 v112, v112, v113
	global_store_dword v[114:115], v112, off
